# score loop: per-iteration wait+barrier+DMA+fragment reads moved from the iteration top to behind the first sub-tile (which only needs registers); exit compare re-issued before its branch
# speedup vs baseline: 1.0071x; 1.0013x over previous
; #define MFMA(a, b, c) __builtin_amdgcn_mfma_f32_32x32x16_bf16((a), (b), (c), 0, 0, 0)
; DI void score_phase(const Params& p, char* smem) {
;     ...
;     for (int nt2 = nt_lo; nt2 < nt_hi; ++nt2) {
;       const int k0 = nt2 * 32;
;       const int kn = (nt2 + 1 < nt_hi) ? (k0 + 32) : k0;
; #pragma unroll
;       for (int st = 0; st < 4; ++st) bnx[st] = *(const bf16x8*)(Hb + (size_t)(kn + r) * HLD + 4096 + st * 16 + 8 * h);
; #pragma unroll
;       for (int rt = 0; rt < 4; ++rt) {
;         f32x16 acc;
; #pragma unroll
;         for (int e = 0; e < 16; ++e) acc[e] = 0.f;
; #pragma unroll
;         for (int st = 0; st < 4; ++st) acc = MFMA(af[rt][st], bfr[st], acc);
;         float s = 0.f;
; #pragma unroll
;         for (int e4 = 0; e4 < 4; ++e4) {
;           const f32x4 wv = *(const f32x4*)(wl + (2 * rt + h) * 16 + e4 * 4);
; #pragma unroll
;           for (int i = 0; i < 4; ++i) s += fmaxf(acc[e4 * 4 + i], 0.f) * wv[i];
;         }
;         const int row = (t0 + 2 * rt + h) - blk * 64;
;         __builtin_nontemporal_store(s, scb + (size_t)row * n + k0 + r);
;       }
; #pragma unroll
;       for (int st = 0; st < 4; ++st) bfr[st] = bnx[st];
.LBB0_822:
	s_add_i32 s15, s15, 1
	s_add_i32 s17, s8, 32
	s_add_i32 s19, s8, 96
	s_add_i32 s18, s15, 2
	s_cmp_lt_i32 s18, s16
	s_cselect_b32 s18, s19, s8
	s_ashr_i32 s9, s8, 31
	v_lshl_add_u64 v[196:197], s[8:9], 2, v[186:187]
	s_mov_b32 s8, s17
	v_mfma_f32_32x32x16_bf16 v[224:239], v[42:45], v[174:177], 0
	v_max_f32_e32 v240, 0, v2
	v_fma_f32 v183, v82, v240, 0
	v_max_f32_e32 v241, 0, v3
	v_fmac_f32_e32 v183, v83, v241
	v_max_f32_e32 v240, 0, v4
	v_fmac_f32_e32 v183, v84, v240
	v_max_f32_e32 v241, 0, v5
	v_fmac_f32_e32 v183, v85, v241
	v_mfma_f32_32x32x16_bf16 v[224:239], v[34:37], v[170:173], v[224:239]
	v_max_f32_e32 v240, 0, v6
	v_fmac_f32_e32 v183, v86, v240
	v_max_f32_e32 v241, 0, v7
	v_fmac_f32_e32 v183, v87, v241
	v_max_f32_e32 v240, 0, v8
	v_fmac_f32_e32 v183, v88, v240
	v_max_f32_e32 v241, 0, v9
	v_fmac_f32_e32 v183, v89, v241
	v_mfma_f32_32x32x16_bf16 v[224:239], v[38:41], v[166:169], v[224:239]
	v_max_f32_e32 v240, 0, v10
	v_fmac_f32_e32 v183, v90, v240
	v_max_f32_e32 v241, 0, v11
	v_fmac_f32_e32 v183, v91, v241
	v_max_f32_e32 v240, 0, v12
	v_fmac_f32_e32 v183, v92, v240
	v_max_f32_e32 v241, 0, v13
	v_fmac_f32_e32 v183, v93, v241
	v_mfma_f32_32x32x16_bf16 v[224:239], v[46:49], v[162:165], v[224:239]
	v_max_f32_e32 v240, 0, v14
	v_fmac_f32_e32 v183, v94, v240
	v_max_f32_e32 v241, 0, v15
	v_fmac_f32_e32 v183, v95, v241
	v_max_f32_e32 v240, 0, v16
	v_fmac_f32_e32 v183, v96, v240
	v_max_f32_e32 v241, 0, v17
	v_fmac_f32_e32 v183, v97, v241
	v_lshl_add_u64 v[242:243], v[188:189], 2, v[196:197]
	global_store_dword v[242:243], v183, off nt
	s_nop 1
	s_waitcnt vmcnt(9)
	s_barrier
	s_cmp_lt_u32 s32, 0x3000
	s_cbranch_scc0 .Lsc_nd0
	s_mul_i32 s98, s18, 0x2a00
	s_add_u32 s98, s98, s6
	s_addc_u32 s99, s7, 0
	s_add_u32 s98, s98, 0x2000
	s_addc_u32 s99, s99, 0
	s_add_i32 m0, s32, 0x0
	s_nop 0
	global_load_lds_dwordx4 v244, s[98:99]
.Lsc_nd0:
	ds_read_b128 v[154:157], v246 offset:4096
	ds_read_b128 v[150:153], v247 offset:4096
	ds_read_b128 v[146:149], v248 offset:4096
	ds_read_b128 v[158:161], v249 offset:4096
	v_mfma_f32_32x32x16_bf16 v[2:17], v[58:61], v[174:177], 0
	v_max_f32_e32 v240, 0, v224
	v_fma_f32 v183, v98, v240, 0
	v_max_f32_e32 v241, 0, v225
	v_fmac_f32_e32 v183, v99, v241
	v_max_f32_e32 v240, 0, v226
	v_fmac_f32_e32 v183, v100, v240
	v_max_f32_e32 v241, 0, v227
	v_fmac_f32_e32 v183, v101, v241
	v_mfma_f32_32x32x16_bf16 v[2:17], v[50:53], v[170:173], v[2:17]
	v_max_f32_e32 v240, 0, v228
	v_fmac_f32_e32 v183, v102, v240
	v_max_f32_e32 v241, 0, v229
	v_fmac_f32_e32 v183, v103, v241
	v_max_f32_e32 v240, 0, v230
	v_fmac_f32_e32 v183, v104, v240
	v_max_f32_e32 v241, 0, v231
	v_fmac_f32_e32 v183, v105, v241
	v_mfma_f32_32x32x16_bf16 v[2:17], v[54:57], v[166:169], v[2:17]
	v_max_f32_e32 v240, 0, v232
	v_fmac_f32_e32 v183, v106, v240
	v_max_f32_e32 v241, 0, v233
	v_fmac_f32_e32 v183, v107, v241
	v_max_f32_e32 v240, 0, v234
	v_fmac_f32_e32 v183, v108, v240
	v_max_f32_e32 v241, 0, v235
	v_fmac_f32_e32 v183, v109, v241
	v_mfma_f32_32x32x16_bf16 v[2:17], v[62:65], v[162:165], v[2:17]
	v_max_f32_e32 v240, 0, v236
	v_fmac_f32_e32 v183, v110, v240
	v_max_f32_e32 v241, 0, v237
	v_fmac_f32_e32 v183, v111, v241
	v_max_f32_e32 v240, 0, v238
	v_fmac_f32_e32 v183, v112, v240
	v_max_f32_e32 v241, 0, v239
	v_fmac_f32_e32 v183, v113, v241
	v_lshl_add_u64 v[242:243], v[190:191], 2, v[196:197]
	global_store_dword v[242:243], v183, off nt
	s_nop 1
	v_mfma_f32_32x32x16_bf16 v[224:239], v[74:77], v[174:177], 0
	v_max_f32_e32 v240, 0, v2
	v_fma_f32 v183, v114, v240, 0
	v_max_f32_e32 v241, 0, v3
	v_fmac_f32_e32 v183, v115, v241
	v_max_f32_e32 v240, 0, v4
	v_fmac_f32_e32 v183, v116, v240
	v_max_f32_e32 v241, 0, v5
	v_fmac_f32_e32 v183, v117, v241
	v_mfma_f32_32x32x16_bf16 v[224:239], v[66:69], v[170:173], v[224:239]
	v_max_f32_e32 v240, 0, v6
	v_fmac_f32_e32 v183, v118, v240
	v_max_f32_e32 v241, 0, v7
	v_fmac_f32_e32 v183, v119, v241
	v_max_f32_e32 v240, 0, v8
	v_fmac_f32_e32 v183, v120, v240
	v_max_f32_e32 v241, 0, v9
	v_fmac_f32_e32 v183, v121, v241
	v_mfma_f32_32x32x16_bf16 v[224:239], v[70:73], v[166:169], v[224:239]
	v_max_f32_e32 v240, 0, v10
	v_fmac_f32_e32 v183, v122, v240
	v_max_f32_e32 v241, 0, v11
	v_fmac_f32_e32 v183, v123, v241
	v_max_f32_e32 v240, 0, v12
	v_fmac_f32_e32 v183, v124, v240
	v_max_f32_e32 v241, 0, v13
	v_fmac_f32_e32 v183, v125, v241
	v_mfma_f32_32x32x16_bf16 v[224:239], v[78:81], v[162:165], v[224:239]
	v_max_f32_e32 v240, 0, v14
	v_fmac_f32_e32 v183, v126, v240
	v_max_f32_e32 v241, 0, v15
	v_fmac_f32_e32 v183, v127, v241
	v_max_f32_e32 v240, 0, v16
	v_fmac_f32_e32 v183, v128, v240
	v_max_f32_e32 v241, 0, v17
	v_fmac_f32_e32 v183, v129, v241
	v_lshl_add_u64 v[242:243], v[192:193], 2, v[196:197]
	global_store_dword v[242:243], v183, off nt
	s_nop 1
	s_waitcnt lgkmcnt(0)
	v_mfma_f32_32x32x16_bf16 v[2:17], v[26:29], v[154:157], 0
	v_max_f32_e32 v240, 0, v224
	v_fma_f32 v183, v130, v240, 0
	v_max_f32_e32 v241, 0, v225
	v_fmac_f32_e32 v183, v131, v241
	v_max_f32_e32 v240, 0, v226
	v_fmac_f32_e32 v183, v132, v240
	v_max_f32_e32 v241, 0, v227
	v_fmac_f32_e32 v183, v133, v241
	v_mfma_f32_32x32x16_bf16 v[2:17], v[18:21], v[150:153], v[2:17]
	v_max_f32_e32 v240, 0, v228
	v_fmac_f32_e32 v183, v134, v240
	v_max_f32_e32 v241, 0, v229
	v_fmac_f32_e32 v183, v135, v241
	v_max_f32_e32 v240, 0, v230
	v_fmac_f32_e32 v183, v136, v240
	v_max_f32_e32 v241, 0, v231
	v_fmac_f32_e32 v183, v137, v241
	v_mfma_f32_32x32x16_bf16 v[2:17], v[22:25], v[146:149], v[2:17]
	v_max_f32_e32 v240, 0, v232
	v_fmac_f32_e32 v183, v138, v240
	v_max_f32_e32 v241, 0, v233
	v_fmac_f32_e32 v183, v139, v241
	v_max_f32_e32 v240, 0, v234
	v_fmac_f32_e32 v183, v140, v240
	v_max_f32_e32 v241, 0, v235
	v_fmac_f32_e32 v183, v141, v241
	v_mfma_f32_32x32x16_bf16 v[2:17], v[30:33], v[158:161], v[2:17]
	v_max_f32_e32 v240, 0, v236
	v_fmac_f32_e32 v183, v142, v240
	v_max_f32_e32 v241, 0, v237
	v_fmac_f32_e32 v183, v143, v241
	v_max_f32_e32 v240, 0, v238
	v_fmac_f32_e32 v183, v144, v240
	v_max_f32_e32 v241, 0, v239
	v_fmac_f32_e32 v183, v145, v241
	v_lshl_add_u64 v[242:243], v[194:195], 2, v[196:197]
	global_store_dword v[242:243], v183, off nt
	s_nop 1
	s_cmp_ge_i32 s15, s16
	s_cbranch_scc1 .LBB0_819
; #define MFMA(a, b, c) __builtin_amdgcn_mfma_f32_32x32x16_bf16((a), (b), (c), 0, 0, 0)
; DI void score_phase(const Params& p, char* smem) {
;     ...
;     for (int nt2 = nt_lo; nt2 < nt_hi; ++nt2) {
;       const int k0 = nt2 * 32;
;       const int kn = (nt2 + 1 < nt_hi) ? (k0 + 32) : k0;
; #pragma unroll
;       for (int st = 0; st < 4; ++st) bnx[st] = *(const bf16x8*)(Hb + (size_t)(kn + r) * HLD + 4096 + st * 16 + 8 * h);
; #pragma unroll
;       for (int rt = 0; rt < 4; ++rt) {
;         f32x16 acc;
; #pragma unroll
;         for (int e = 0; e < 16; ++e) acc[e] = 0.f;
; #pragma unroll
;         for (int st = 0; st < 4; ++st) acc = MFMA(af[rt][st], bfr[st], acc);
;         float s = 0.f;
; #pragma unroll
;         for (int e4 = 0; e4 < 4; ++e4) {
;           const f32x4 wv = *(const f32x4*)(wl + (2 * rt + h) * 16 + e4 * 4);
; #pragma unroll
;           for (int i = 0; i < 4; ++i) s += fmaxf(acc[e4 * 4 + i], 0.f) * wv[i];
;         }
;         const int row = (t0 + 2 * rt + h) - blk * 64;
;         __builtin_nontemporal_store(s, scb + (size_t)row * n + k0 + r);
;       }
; #pragma unroll
;       for (int st = 0; st < 4; ++st) bfr[st] = bnx[st];
	s_add_i32 s15, s15, 1
	s_add_i32 s17, s8, 32
	s_add_i32 s19, s8, 96
	s_add_i32 s18, s15, 2
	s_cmp_lt_i32 s18, s16
	s_cselect_b32 s18, s19, s8
	s_ashr_i32 s9, s8, 31
	v_lshl_add_u64 v[196:197], s[8:9], 2, v[186:187]
	s_mov_b32 s8, s17
	v_mfma_f32_32x32x16_bf16 v[224:239], v[42:45], v[154:157], 0
	v_max_f32_e32 v240, 0, v2
	v_fma_f32 v183, v82, v240, 0
	v_max_f32_e32 v241, 0, v3
	v_fmac_f32_e32 v183, v83, v241
	v_max_f32_e32 v240, 0, v4
	v_fmac_f32_e32 v183, v84, v240
	v_max_f32_e32 v241, 0, v5
	v_fmac_f32_e32 v183, v85, v241
	v_mfma_f32_32x32x16_bf16 v[224:239], v[34:37], v[150:153], v[224:239]
	v_max_f32_e32 v240, 0, v6
	v_fmac_f32_e32 v183, v86, v240
	v_max_f32_e32 v241, 0, v7
	v_fmac_f32_e32 v183, v87, v241
	v_max_f32_e32 v240, 0, v8
	v_fmac_f32_e32 v183, v88, v240
	v_max_f32_e32 v241, 0, v9
	v_fmac_f32_e32 v183, v89, v241
	v_mfma_f32_32x32x16_bf16 v[224:239], v[38:41], v[146:149], v[224:239]
	v_max_f32_e32 v240, 0, v10
	v_fmac_f32_e32 v183, v90, v240
	v_max_f32_e32 v241, 0, v11
	v_fmac_f32_e32 v183, v91, v241
	v_max_f32_e32 v240, 0, v12
	v_fmac_f32_e32 v183, v92, v240
	v_max_f32_e32 v241, 0, v13
	v_fmac_f32_e32 v183, v93, v241
	v_mfma_f32_32x32x16_bf16 v[224:239], v[46:49], v[158:161], v[224:239]
	v_max_f32_e32 v240, 0, v14
	v_fmac_f32_e32 v183, v94, v240
	v_max_f32_e32 v241, 0, v15
	v_fmac_f32_e32 v183, v95, v241
	v_max_f32_e32 v240, 0, v16
	v_fmac_f32_e32 v183, v96, v240
	v_max_f32_e32 v241, 0, v17
	v_fmac_f32_e32 v183, v97, v241
	v_lshl_add_u64 v[242:243], v[188:189], 2, v[196:197]
	global_store_dword v[242:243], v183, off nt
	s_nop 1
	s_waitcnt vmcnt(9)
	s_barrier
	s_cmp_lt_u32 s32, 0x3000
	s_cbranch_scc0 .Lsc_nd1
	s_mul_i32 s98, s18, 0x2a00
	s_add_u32 s98, s98, s6
	s_addc_u32 s99, s7, 0
	s_add_u32 s98, s98, 0x2000
	s_addc_u32 s99, s99, 0
	s_add_i32 m0, s32, 0x1000
	s_nop 0
	global_load_lds_dwordx4 v244, s[98:99]
.Lsc_nd1:
	ds_read_b128 v[204:207], v246 offset:8192
	ds_read_b128 v[208:211], v247 offset:8192
	ds_read_b128 v[212:215], v248 offset:8192
	ds_read_b128 v[250:253], v249 offset:8192
	v_mfma_f32_32x32x16_bf16 v[2:17], v[58:61], v[154:157], 0
	v_max_f32_e32 v240, 0, v224
	v_fma_f32 v183, v98, v240, 0
	v_max_f32_e32 v241, 0, v225
	v_fmac_f32_e32 v183, v99, v241
	v_max_f32_e32 v240, 0, v226
	v_fmac_f32_e32 v183, v100, v240
	v_max_f32_e32 v241, 0, v227
	v_fmac_f32_e32 v183, v101, v241
	v_mfma_f32_32x32x16_bf16 v[2:17], v[50:53], v[150:153], v[2:17]
	v_max_f32_e32 v240, 0, v228
	v_fmac_f32_e32 v183, v102, v240
	v_max_f32_e32 v241, 0, v229
	v_fmac_f32_e32 v183, v103, v241
	v_max_f32_e32 v240, 0, v230
	v_fmac_f32_e32 v183, v104, v240
	v_max_f32_e32 v241, 0, v231
	v_fmac_f32_e32 v183, v105, v241
	v_mfma_f32_32x32x16_bf16 v[2:17], v[54:57], v[146:149], v[2:17]
	v_max_f32_e32 v240, 0, v232
	v_fmac_f32_e32 v183, v106, v240
	v_max_f32_e32 v241, 0, v233
	v_fmac_f32_e32 v183, v107, v241
	v_max_f32_e32 v240, 0, v234
	v_fmac_f32_e32 v183, v108, v240
	v_max_f32_e32 v241, 0, v235
	v_fmac_f32_e32 v183, v109, v241
	v_mfma_f32_32x32x16_bf16 v[2:17], v[62:65], v[158:161], v[2:17]
	v_max_f32_e32 v240, 0, v236
	v_fmac_f32_e32 v183, v110, v240
	v_max_f32_e32 v241, 0, v237
	v_fmac_f32_e32 v183, v111, v241
	v_max_f32_e32 v240, 0, v238
	v_fmac_f32_e32 v183, v112, v240
	v_max_f32_e32 v241, 0, v239
	v_fmac_f32_e32 v183, v113, v241
	v_lshl_add_u64 v[242:243], v[190:191], 2, v[196:197]
	global_store_dword v[242:243], v183, off nt
	s_nop 1
	v_mfma_f32_32x32x16_bf16 v[224:239], v[74:77], v[154:157], 0
	v_max_f32_e32 v240, 0, v2
	v_fma_f32 v183, v114, v240, 0
	v_max_f32_e32 v241, 0, v3
	v_fmac_f32_e32 v183, v115, v241
	v_max_f32_e32 v240, 0, v4
	v_fmac_f32_e32 v183, v116, v240
	v_max_f32_e32 v241, 0, v5
	v_fmac_f32_e32 v183, v117, v241
	v_mfma_f32_32x32x16_bf16 v[224:239], v[66:69], v[150:153], v[224:239]
	v_max_f32_e32 v240, 0, v6
	v_fmac_f32_e32 v183, v118, v240
	v_max_f32_e32 v241, 0, v7
	v_fmac_f32_e32 v183, v119, v241
	v_max_f32_e32 v240, 0, v8
	v_fmac_f32_e32 v183, v120, v240
	v_max_f32_e32 v241, 0, v9
	v_fmac_f32_e32 v183, v121, v241
	v_mfma_f32_32x32x16_bf16 v[224:239], v[70:73], v[146:149], v[224:239]
	v_max_f32_e32 v240, 0, v10
	v_fmac_f32_e32 v183, v122, v240
	v_max_f32_e32 v241, 0, v11
	v_fmac_f32_e32 v183, v123, v241
	v_max_f32_e32 v240, 0, v12
	v_fmac_f32_e32 v183, v124, v240
	v_max_f32_e32 v241, 0, v13
	v_fmac_f32_e32 v183, v125, v241
	v_mfma_f32_32x32x16_bf16 v[224:239], v[78:81], v[158:161], v[224:239]
	v_max_f32_e32 v240, 0, v14
	v_fmac_f32_e32 v183, v126, v240
	v_max_f32_e32 v241, 0, v15
	v_fmac_f32_e32 v183, v127, v241
	v_max_f32_e32 v240, 0, v16
	v_fmac_f32_e32 v183, v128, v240
	v_max_f32_e32 v241, 0, v17
	v_fmac_f32_e32 v183, v129, v241
	v_lshl_add_u64 v[242:243], v[192:193], 2, v[196:197]
	global_store_dword v[242:243], v183, off nt
	s_nop 1
	s_waitcnt lgkmcnt(0)
	v_mfma_f32_32x32x16_bf16 v[2:17], v[26:29], v[204:207], 0
	v_max_f32_e32 v240, 0, v224
	v_fma_f32 v183, v130, v240, 0
	v_max_f32_e32 v241, 0, v225
	v_fmac_f32_e32 v183, v131, v241
	v_max_f32_e32 v240, 0, v226
	v_fmac_f32_e32 v183, v132, v240
	v_max_f32_e32 v241, 0, v227
	v_fmac_f32_e32 v183, v133, v241
	v_mfma_f32_32x32x16_bf16 v[2:17], v[18:21], v[208:211], v[2:17]
	v_max_f32_e32 v240, 0, v228
	v_fmac_f32_e32 v183, v134, v240
	v_max_f32_e32 v241, 0, v229
	v_fmac_f32_e32 v183, v135, v241
	v_max_f32_e32 v240, 0, v230
	v_fmac_f32_e32 v183, v136, v240
	v_max_f32_e32 v241, 0, v231
	v_fmac_f32_e32 v183, v137, v241
	v_mfma_f32_32x32x16_bf16 v[2:17], v[22:25], v[212:215], v[2:17]
	v_max_f32_e32 v240, 0, v232
	v_fmac_f32_e32 v183, v138, v240
	v_max_f32_e32 v241, 0, v233
	v_fmac_f32_e32 v183, v139, v241
	v_max_f32_e32 v240, 0, v234
	v_fmac_f32_e32 v183, v140, v240
	v_max_f32_e32 v241, 0, v235
	v_fmac_f32_e32 v183, v141, v241
	v_mfma_f32_32x32x16_bf16 v[2:17], v[30:33], v[250:253], v[2:17]
	v_max_f32_e32 v240, 0, v236
	v_fmac_f32_e32 v183, v142, v240
	v_max_f32_e32 v241, 0, v237
	v_fmac_f32_e32 v183, v143, v241
	v_max_f32_e32 v240, 0, v238
	v_fmac_f32_e32 v183, v144, v240
	v_max_f32_e32 v241, 0, v239
	v_fmac_f32_e32 v183, v145, v241
	v_lshl_add_u64 v[242:243], v[194:195], 2, v[196:197]
	global_store_dword v[242:243], v183, off nt
	s_nop 1
	s_cmp_ge_i32 s15, s16
	s_cbranch_scc1 .LBB0_819
; #define MFMA(a, b, c) __builtin_amdgcn_mfma_f32_32x32x16_bf16((a), (b), (c), 0, 0, 0)
; DI void score_phase(const Params& p, char* smem) {
;     ...
;     for (int nt2 = nt_lo; nt2 < nt_hi; ++nt2) {
;       const int k0 = nt2 * 32;
;       const int kn = (nt2 + 1 < nt_hi) ? (k0 + 32) : k0;
; #pragma unroll
;       for (int st = 0; st < 4; ++st) bnx[st] = *(const bf16x8*)(Hb + (size_t)(kn + r) * HLD + 4096 + st * 16 + 8 * h);
; #pragma unroll
;       for (int rt = 0; rt < 4; ++rt) {
;         f32x16 acc;
; #pragma unroll
;         for (int e = 0; e < 16; ++e) acc[e] = 0.f;
; #pragma unroll
;         for (int st = 0; st < 4; ++st) acc = MFMA(af[rt][st], bfr[st], acc);
;         float s = 0.f;
; #pragma unroll
;         for (int e4 = 0; e4 < 4; ++e4) {
;           const f32x4 wv = *(const f32x4*)(wl + (2 * rt + h) * 16 + e4 * 4);
; #pragma unroll
;           for (int i = 0; i < 4; ++i) s += fmaxf(acc[e4 * 4 + i], 0.f) * wv[i];
;         }
;         const int row = (t0 + 2 * rt + h) - blk * 64;
;         __builtin_nontemporal_store(s, scb + (size_t)row * n + k0 + r);
;       }
; #pragma unroll
;       for (int st = 0; st < 4; ++st) bfr[st] = bnx[st];
	s_add_i32 s15, s15, 1
	s_add_i32 s17, s8, 32
	s_add_i32 s19, s8, 96
	s_add_i32 s18, s15, 2
	s_cmp_lt_i32 s18, s16
	s_cselect_b32 s18, s19, s8
	s_ashr_i32 s9, s8, 31
	v_lshl_add_u64 v[196:197], s[8:9], 2, v[186:187]
	s_mov_b32 s8, s17
	v_mfma_f32_32x32x16_bf16 v[224:239], v[42:45], v[204:207], 0
	v_max_f32_e32 v240, 0, v2
	v_fma_f32 v183, v82, v240, 0
	v_max_f32_e32 v241, 0, v3
	v_fmac_f32_e32 v183, v83, v241
	v_max_f32_e32 v240, 0, v4
	v_fmac_f32_e32 v183, v84, v240
	v_max_f32_e32 v241, 0, v5
	v_fmac_f32_e32 v183, v85, v241
	v_mfma_f32_32x32x16_bf16 v[224:239], v[34:37], v[208:211], v[224:239]
	v_max_f32_e32 v240, 0, v6
	v_fmac_f32_e32 v183, v86, v240
	v_max_f32_e32 v241, 0, v7
	v_fmac_f32_e32 v183, v87, v241
	v_max_f32_e32 v240, 0, v8
	v_fmac_f32_e32 v183, v88, v240
	v_max_f32_e32 v241, 0, v9
	v_fmac_f32_e32 v183, v89, v241
	v_mfma_f32_32x32x16_bf16 v[224:239], v[38:41], v[212:215], v[224:239]
	v_max_f32_e32 v240, 0, v10
	v_fmac_f32_e32 v183, v90, v240
	v_max_f32_e32 v241, 0, v11
	v_fmac_f32_e32 v183, v91, v241
	v_max_f32_e32 v240, 0, v12
	v_fmac_f32_e32 v183, v92, v240
	v_max_f32_e32 v241, 0, v13
	v_fmac_f32_e32 v183, v93, v241
	v_mfma_f32_32x32x16_bf16 v[224:239], v[46:49], v[250:253], v[224:239]
	v_max_f32_e32 v240, 0, v14
	v_fmac_f32_e32 v183, v94, v240
	v_max_f32_e32 v241, 0, v15
	v_fmac_f32_e32 v183, v95, v241
	v_max_f32_e32 v240, 0, v16
	v_fmac_f32_e32 v183, v96, v240
	v_max_f32_e32 v241, 0, v17
	v_fmac_f32_e32 v183, v97, v241
	v_lshl_add_u64 v[242:243], v[188:189], 2, v[196:197]
	global_store_dword v[242:243], v183, off nt
	s_nop 1
	s_waitcnt vmcnt(9)
	s_barrier
	s_cmp_lt_u32 s32, 0x3000
	s_cbranch_scc0 .Lsc_nd2
	s_mul_i32 s98, s18, 0x2a00
	s_add_u32 s98, s98, s6
	s_addc_u32 s99, s7, 0
	s_add_u32 s98, s98, 0x2000
	s_addc_u32 s99, s99, 0
	s_add_i32 m0, s32, 0x2000
	s_nop 0
	global_load_lds_dwordx4 v244, s[98:99]
.Lsc_nd2:
	ds_read_b128 v[174:177], v246 offset:0
	ds_read_b128 v[170:173], v247 offset:0
	ds_read_b128 v[166:169], v248 offset:0
	ds_read_b128 v[162:165], v249 offset:0
	v_mfma_f32_32x32x16_bf16 v[2:17], v[58:61], v[204:207], 0
	v_max_f32_e32 v240, 0, v224
	v_fma_f32 v183, v98, v240, 0
	v_max_f32_e32 v241, 0, v225
	v_fmac_f32_e32 v183, v99, v241
	v_max_f32_e32 v240, 0, v226
	v_fmac_f32_e32 v183, v100, v240
	v_max_f32_e32 v241, 0, v227
	v_fmac_f32_e32 v183, v101, v241
	v_mfma_f32_32x32x16_bf16 v[2:17], v[50:53], v[208:211], v[2:17]
	v_max_f32_e32 v240, 0, v228
	v_fmac_f32_e32 v183, v102, v240
	v_max_f32_e32 v241, 0, v229
	v_fmac_f32_e32 v183, v103, v241
	v_max_f32_e32 v240, 0, v230
	v_fmac_f32_e32 v183, v104, v240
	v_max_f32_e32 v241, 0, v231
	v_fmac_f32_e32 v183, v105, v241
	v_mfma_f32_32x32x16_bf16 v[2:17], v[54:57], v[212:215], v[2:17]
	v_max_f32_e32 v240, 0, v232
	v_fmac_f32_e32 v183, v106, v240
	v_max_f32_e32 v241, 0, v233
	v_fmac_f32_e32 v183, v107, v241
	v_max_f32_e32 v240, 0, v234
	v_fmac_f32_e32 v183, v108, v240
	v_max_f32_e32 v241, 0, v235
	v_fmac_f32_e32 v183, v109, v241
	v_mfma_f32_32x32x16_bf16 v[2:17], v[62:65], v[250:253], v[2:17]
	v_max_f32_e32 v240, 0, v236
	v_fmac_f32_e32 v183, v110, v240
	v_max_f32_e32 v241, 0, v237
	v_fmac_f32_e32 v183, v111, v241
	v_max_f32_e32 v240, 0, v238
	v_fmac_f32_e32 v183, v112, v240
	v_max_f32_e32 v241, 0, v239
	v_fmac_f32_e32 v183, v113, v241
	v_lshl_add_u64 v[242:243], v[190:191], 2, v[196:197]
	global_store_dword v[242:243], v183, off nt
	s_nop 1
	v_mfma_f32_32x32x16_bf16 v[224:239], v[74:77], v[204:207], 0
	v_max_f32_e32 v240, 0, v2
	v_fma_f32 v183, v114, v240, 0
	v_max_f32_e32 v241, 0, v3
	v_fmac_f32_e32 v183, v115, v241
	v_max_f32_e32 v240, 0, v4
	v_fmac_f32_e32 v183, v116, v240
	v_max_f32_e32 v241, 0, v5
	v_fmac_f32_e32 v183, v117, v241
	v_mfma_f32_32x32x16_bf16 v[224:239], v[66:69], v[208:211], v[224:239]
	v_max_f32_e32 v240, 0, v6
	v_fmac_f32_e32 v183, v118, v240
	v_max_f32_e32 v241, 0, v7
	v_fmac_f32_e32 v183, v119, v241
	v_max_f32_e32 v240, 0, v8
	v_fmac_f32_e32 v183, v120, v240
	v_max_f32_e32 v241, 0, v9
	v_fmac_f32_e32 v183, v121, v241
	v_mfma_f32_32x32x16_bf16 v[224:239], v[70:73], v[212:215], v[224:239]
	v_max_f32_e32 v240, 0, v10
	v_fmac_f32_e32 v183, v122, v240
	v_max_f32_e32 v241, 0, v11
	v_fmac_f32_e32 v183, v123, v241
	v_max_f32_e32 v240, 0, v12
	v_fmac_f32_e32 v183, v124, v240
	v_max_f32_e32 v241, 0, v13
	v_fmac_f32_e32 v183, v125, v241
	v_mfma_f32_32x32x16_bf16 v[224:239], v[78:81], v[250:253], v[224:239]
	v_max_f32_e32 v240, 0, v14
	v_fmac_f32_e32 v183, v126, v240
	v_max_f32_e32 v241, 0, v15
	v_fmac_f32_e32 v183, v127, v241
	v_max_f32_e32 v240, 0, v16
	v_fmac_f32_e32 v183, v128, v240
	v_max_f32_e32 v241, 0, v17
	v_fmac_f32_e32 v183, v129, v241
	v_lshl_add_u64 v[242:243], v[192:193], 2, v[196:197]
	global_store_dword v[242:243], v183, off nt
	s_nop 1
	s_waitcnt lgkmcnt(0)
	v_mfma_f32_32x32x16_bf16 v[2:17], v[26:29], v[174:177], 0
	v_max_f32_e32 v240, 0, v224
	v_fma_f32 v183, v130, v240, 0
	v_max_f32_e32 v241, 0, v225
	v_fmac_f32_e32 v183, v131, v241
	v_max_f32_e32 v240, 0, v226
	v_fmac_f32_e32 v183, v132, v240
	v_max_f32_e32 v241, 0, v227
	v_fmac_f32_e32 v183, v133, v241
	v_mfma_f32_32x32x16_bf16 v[2:17], v[18:21], v[170:173], v[2:17]
	v_max_f32_e32 v240, 0, v228
	v_fmac_f32_e32 v183, v134, v240
	v_max_f32_e32 v241, 0, v229
	v_fmac_f32_e32 v183, v135, v241
	v_max_f32_e32 v240, 0, v230
	v_fmac_f32_e32 v183, v136, v240
	v_max_f32_e32 v241, 0, v231
	v_fmac_f32_e32 v183, v137, v241
	v_mfma_f32_32x32x16_bf16 v[2:17], v[22:25], v[166:169], v[2:17]
	v_max_f32_e32 v240, 0, v232
	v_fmac_f32_e32 v183, v138, v240
	v_max_f32_e32 v241, 0, v233
	v_fmac_f32_e32 v183, v139, v241
	v_max_f32_e32 v240, 0, v234
	v_fmac_f32_e32 v183, v140, v240
	v_max_f32_e32 v241, 0, v235
	v_fmac_f32_e32 v183, v141, v241
	v_mfma_f32_32x32x16_bf16 v[2:17], v[30:33], v[162:165], v[2:17]
	v_max_f32_e32 v240, 0, v236
	v_fmac_f32_e32 v183, v142, v240
	v_max_f32_e32 v241, 0, v237
	v_fmac_f32_e32 v183, v143, v241
	v_max_f32_e32 v240, 0, v238
	v_fmac_f32_e32 v183, v144, v240
	v_max_f32_e32 v241, 0, v239
	v_fmac_f32_e32 v183, v145, v241
	v_lshl_add_u64 v[242:243], v[194:195], 2, v[196:197]
	global_store_dword v[242:243], v183, off nt
	s_nop 1
	s_cmp_ge_i32 s15, s16
	s_cbranch_scc0 .LBB0_822
	s_branch .LBB0_819
